# last-layer ffn2 residual epilogue (no next-norm output): serialized load-wait-fma-store ladder replaced by the pipelined counted-wait form
# baseline (speedup 1.0000x reference)
;     __device__ __forceinline__ void operator()(const f32x4 (&acc)[2][2][4][2], const Unit& u, int wr, int wc, int fr, int fq) const {
;     ...
;             for (int m = 0; m < 4; ++m) { const size_t row = rowb + ai * HALF + m * 16; const size_t off = row * 1024 + col0; float s = 0.f;
; #pragma unroll
;                 for (int bj = 0; bj < 2; ++bj) { u32x2 w[2];
; #pragma unroll
;                     for (int n = 0; n < 2; ++n) { const f32x4 xv = *(const __attribute__((address_space(1))) f32x4*)(xin + off + bj * HALF + n * 16);
;                         const f32x4 xn = xv + gv[bj][n] * acc[ai][bj][m][n];
;                         *(__attribute__((address_space(1))) f32x4*)(out + off + bj * HALF + n * 16) = xn;
.Lepi_ffn2_noxg:
	v_lshlrev_b32_e32 v164, 2, v164
	v_lshl_add_u32 v164, v174, 12, v164
	v_mov_b32_e32 v175, v164
	global_load_dwordx4 v[182:185], v175, s[2:3] offset:0
	global_load_dwordx4 v[186:189], v175, s[2:3] offset:64
	global_load_dwordx4 v[190:193], v175, s[2:3] offset:512
	global_load_dwordx4 v[194:197], v175, s[2:3] offset:576
	v_add_u32_e32 v175, 0x10000, v175
	global_load_dwordx4 v[198:201], v175, s[2:3] offset:0
	global_load_dwordx4 v[202:205], v175, s[2:3] offset:64
	global_load_dwordx4 v[236:239], v175, s[2:3] offset:512
	global_load_dwordx4 v[240:243], v175, s[2:3] offset:576
	v_add_u32_e32 v175, 0x10000, v175
	global_load_dwordx4 v[244:247], v175, s[2:3] offset:0
	global_load_dwordx4 v[248:251], v175, s[2:3] offset:64
	s_waitcnt vmcnt(8)
	v_pk_fma_f32 v[182:183], v[64:65], v[72:73], v[182:183]
	v_pk_fma_f32 v[184:185], v[66:67], v[74:75], v[184:185]
	v_pk_fma_f32 v[186:187], v[144:145], v[76:77], v[186:187]
	v_pk_fma_f32 v[188:189], v[146:147], v[78:79], v[188:189]
	global_store_dwordx4 v164, v[182:185], s[2:3] offset:0
	global_store_dwordx4 v164, v[186:189], s[2:3] offset:64
	global_load_dwordx4 v[64:67], v175, s[2:3] offset:512
	global_load_dwordx4 v[144:147], v175, s[2:3] offset:576
	v_add_u32_e32 v175, 0x10000, v175
	s_waitcnt vmcnt(10)
	v_pk_fma_f32 v[190:191], v[140:141], v[60:61], v[190:191]
	v_pk_fma_f32 v[192:193], v[142:143], v[62:63], v[192:193]
	v_pk_fma_f32 v[194:195], v[136:137], v[56:57], v[194:195]
	v_pk_fma_f32 v[196:197], v[138:139], v[58:59], v[196:197]
	global_store_dwordx4 v164, v[190:193], s[2:3] offset:512
	global_store_dwordx4 v164, v[194:197], s[2:3] offset:576
	global_load_dwordx4 v[140:143], v175, s[2:3] offset:0
	global_load_dwordx4 v[136:139], v175, s[2:3] offset:64
	v_add_u32_e32 v164, 0x10000, v164
	s_waitcnt vmcnt(12)
	v_pk_fma_f32 v[198:199], v[132:133], v[72:73], v[198:199]
	v_pk_fma_f32 v[200:201], v[134:135], v[74:75], v[200:201]
	v_pk_fma_f32 v[202:203], v[128:129], v[76:77], v[202:203]
	v_pk_fma_f32 v[204:205], v[130:131], v[78:79], v[204:205]
	global_store_dwordx4 v164, v[198:201], s[2:3] offset:0
	global_store_dwordx4 v164, v[202:205], s[2:3] offset:64
	global_load_dwordx4 v[132:135], v175, s[2:3] offset:512
	global_load_dwordx4 v[128:131], v175, s[2:3] offset:576
	v_add_u32_e32 v175, 0x50000, v175
	s_waitcnt vmcnt(14)
	v_pk_fma_f32 v[236:237], v[124:125], v[60:61], v[236:237]
	v_pk_fma_f32 v[238:239], v[126:127], v[62:63], v[238:239]
	v_pk_fma_f32 v[240:241], v[120:121], v[56:57], v[240:241]
	v_pk_fma_f32 v[242:243], v[122:123], v[58:59], v[242:243]
	global_store_dwordx4 v164, v[236:239], s[2:3] offset:512
	global_store_dwordx4 v164, v[240:243], s[2:3] offset:576
	global_load_dwordx4 v[124:127], v175, s[2:3] offset:0
	global_load_dwordx4 v[120:123], v175, s[2:3] offset:64
	v_add_u32_e32 v164, 0x10000, v164
	s_waitcnt vmcnt(16)
	v_pk_fma_f32 v[244:245], v[116:117], v[72:73], v[244:245]
	v_pk_fma_f32 v[246:247], v[118:119], v[74:75], v[246:247]
	v_pk_fma_f32 v[248:249], v[112:113], v[76:77], v[248:249]
	v_pk_fma_f32 v[250:251], v[114:115], v[78:79], v[250:251]
	global_store_dwordx4 v164, v[244:247], s[2:3] offset:0
	global_store_dwordx4 v164, v[248:251], s[2:3] offset:64
	global_load_dwordx4 v[116:119], v175, s[2:3] offset:512
	global_load_dwordx4 v[112:115], v175, s[2:3] offset:576
	v_add_u32_e32 v175, 0x10000, v175
	s_waitcnt vmcnt(16)
	v_pk_fma_f32 v[64:65], v[108:109], v[60:61], v[64:65]
	v_pk_fma_f32 v[66:67], v[110:111], v[62:63], v[66:67]
	v_pk_fma_f32 v[144:145], v[104:105], v[56:57], v[144:145]
	v_pk_fma_f32 v[146:147], v[106:107], v[58:59], v[146:147]
	global_store_dwordx4 v164, v[64:67], s[2:3] offset:512
	global_store_dwordx4 v164, v[144:147], s[2:3] offset:576
	global_load_dwordx4 v[108:111], v175, s[2:3] offset:0
	global_load_dwordx4 v[104:107], v175, s[2:3] offset:64
	v_add_u32_e32 v164, 0x10000, v164
	s_waitcnt vmcnt(16)
;     __device__ __forceinline__ void operator()(const f32x4 (&acc)[2][2][4][2], const Unit& u, int wr, int wc, int fr, int fq) const {
;     ...
;             for (int m = 0; m < 4; ++m) { const size_t row = rowb + ai * HALF + m * 16; const size_t off = row * 1024 + col0; float s = 0.f;
; #pragma unroll
;                 for (int bj = 0; bj < 2; ++bj) { u32x2 w[2];
; #pragma unroll
;                     for (int n = 0; n < 2; ++n) { const f32x4 xv = *(const __attribute__((address_space(1))) f32x4*)(xin + off + bj * HALF + n * 16);
;                         const f32x4 xn = xv + gv[bj][n] * acc[ai][bj][m][n];
;                         *(__attribute__((address_space(1))) f32x4*)(out + off + bj * HALF + n * 16) = xn;
	v_pk_fma_f32 v[140:141], v[100:101], v[72:73], v[140:141]
	v_pk_fma_f32 v[142:143], v[102:103], v[74:75], v[142:143]
	v_pk_fma_f32 v[136:137], v[96:97], v[76:77], v[136:137]
	v_pk_fma_f32 v[138:139], v[98:99], v[78:79], v[138:139]
	global_store_dwordx4 v164, v[140:143], s[2:3] offset:0
	global_store_dwordx4 v164, v[136:139], s[2:3] offset:64
	global_load_dwordx4 v[100:103], v175, s[2:3] offset:512
	global_load_dwordx4 v[96:99], v175, s[2:3] offset:576
	v_add_u32_e32 v175, 0x10000, v175
	s_waitcnt vmcnt(16)
	v_pk_fma_f32 v[132:133], v[92:93], v[60:61], v[132:133]
	v_pk_fma_f32 v[134:135], v[94:95], v[62:63], v[134:135]
	v_pk_fma_f32 v[128:129], v[88:89], v[56:57], v[128:129]
	v_pk_fma_f32 v[130:131], v[90:91], v[58:59], v[130:131]
	global_store_dwordx4 v164, v[132:135], s[2:3] offset:512
	global_store_dwordx4 v164, v[128:131], s[2:3] offset:576
	global_load_dwordx4 v[92:95], v175, s[2:3] offset:0
	global_load_dwordx4 v[88:91], v175, s[2:3] offset:64
	v_add_u32_e32 v164, 0x50000, v164
	s_waitcnt vmcnt(16)
	v_pk_fma_f32 v[124:125], v[84:85], v[72:73], v[124:125]
	v_pk_fma_f32 v[126:127], v[86:87], v[74:75], v[126:127]
	v_pk_fma_f32 v[120:121], v[80:81], v[76:77], v[120:121]
	v_pk_fma_f32 v[122:123], v[82:83], v[78:79], v[122:123]
	global_store_dwordx4 v164, v[124:127], s[2:3] offset:0
	global_store_dwordx4 v164, v[120:123], s[2:3] offset:64
	global_load_dwordx4 v[84:87], v175, s[2:3] offset:512
	global_load_dwordx4 v[80:83], v175, s[2:3] offset:576
	v_add_u32_e32 v175, 0x10000, v175
	s_waitcnt vmcnt(16)
	v_pk_fma_f32 v[116:117], v[68:69], v[60:61], v[116:117]
	v_pk_fma_f32 v[118:119], v[70:71], v[62:63], v[118:119]
	v_pk_fma_f32 v[112:113], v[52:53], v[56:57], v[112:113]
	v_pk_fma_f32 v[114:115], v[54:55], v[58:59], v[114:115]
	global_store_dwordx4 v164, v[116:119], s[2:3] offset:512
	global_store_dwordx4 v164, v[112:115], s[2:3] offset:576
	global_load_dwordx4 v[68:71], v175, s[2:3] offset:0
	global_load_dwordx4 v[52:55], v175, s[2:3] offset:64
	v_add_u32_e32 v164, 0x10000, v164
	s_waitcnt vmcnt(16)
	v_pk_fma_f32 v[108:109], v[48:49], v[72:73], v[108:109]
	v_pk_fma_f32 v[110:111], v[50:51], v[74:75], v[110:111]
	v_pk_fma_f32 v[104:105], v[44:45], v[76:77], v[104:105]
	v_pk_fma_f32 v[106:107], v[46:47], v[78:79], v[106:107]
	global_store_dwordx4 v164, v[108:111], s[2:3] offset:0
	global_store_dwordx4 v164, v[104:107], s[2:3] offset:64
	global_load_dwordx4 v[48:51], v175, s[2:3] offset:512
	global_load_dwordx4 v[44:47], v175, s[2:3] offset:576
	s_waitcnt vmcnt(16)
	v_pk_fma_f32 v[100:101], v[40:41], v[60:61], v[100:101]
	v_pk_fma_f32 v[102:103], v[42:43], v[62:63], v[102:103]
	v_pk_fma_f32 v[96:97], v[36:37], v[56:57], v[96:97]
	v_pk_fma_f32 v[98:99], v[38:39], v[58:59], v[98:99]
	global_store_dwordx4 v164, v[100:103], s[2:3] offset:512
	global_store_dwordx4 v164, v[96:99], s[2:3] offset:576
	v_add_u32_e32 v164, 0x10000, v164
	s_waitcnt vmcnt(14)
	v_pk_fma_f32 v[92:93], v[32:33], v[72:73], v[92:93]
	v_pk_fma_f32 v[94:95], v[34:35], v[74:75], v[94:95]
	v_pk_fma_f32 v[88:89], v[28:29], v[76:77], v[88:89]
	v_pk_fma_f32 v[90:91], v[30:31], v[78:79], v[90:91]
	global_store_dwordx4 v164, v[92:95], s[2:3] offset:0
	global_store_dwordx4 v164, v[88:91], s[2:3] offset:64
	s_waitcnt vmcnt(12)
	v_pk_fma_f32 v[84:85], v[24:25], v[60:61], v[84:85]
	v_pk_fma_f32 v[86:87], v[26:27], v[62:63], v[86:87]
	v_pk_fma_f32 v[80:81], v[20:21], v[56:57], v[80:81]
	v_pk_fma_f32 v[82:83], v[22:23], v[58:59], v[82:83]
	global_store_dwordx4 v164, v[84:87], s[2:3] offset:512
	global_store_dwordx4 v164, v[80:83], s[2:3] offset:576
	v_add_u32_e32 v164, 0x10000, v164
	s_waitcnt vmcnt(10)
	v_pk_fma_f32 v[68:69], v[16:17], v[72:73], v[68:69]
	v_pk_fma_f32 v[70:71], v[18:19], v[74:75], v[70:71]
	v_pk_fma_f32 v[52:53], v[12:13], v[76:77], v[52:53]
	v_pk_fma_f32 v[54:55], v[14:15], v[78:79], v[54:55]
	global_store_dwordx4 v164, v[68:71], s[2:3] offset:0
	global_store_dwordx4 v164, v[52:55], s[2:3] offset:64
	s_waitcnt vmcnt(8)
	v_pk_fma_f32 v[48:49], v[8:9], v[60:61], v[48:49]
	v_pk_fma_f32 v[50:51], v[10:11], v[62:63], v[50:51]
	v_pk_fma_f32 v[44:45], v[4:5], v[56:57], v[44:45]
	v_pk_fma_f32 v[46:47], v[6:7], v[58:59], v[46:47]
	global_store_dwordx4 v164, v[48:51], s[2:3] offset:512
	global_store_dwordx4 v164, v[44:47], s[2:3] offset:576
	s_branch .LBB0_823
